# grid barrier after the attention phase becomes an XCD-local barrier; the MLP-up phase (whose output overlays Q/K/V) additionally waits on a global attention-done counter
# speedup vs baseline: 1.0084x; 1.0084x over previous
; __device__ __forceinline__ unsigned xb_ld(unsigned* p)              { return __hip_atomic_load(p, __ATOMIC_RELAXED, __HIP_MEMORY_SCOPE_AGENT); }
; __device__ __forceinline__ unsigned xb_add(unsigned* p, unsigned v) { return __hip_atomic_fetch_add(p, v, __ATOMIC_RELAXED, __HIP_MEMORY_SCOPE_AGENT); }
; #define XB_SPIN(cond, bar) do { unsigned _sp = 0; while (cond) { __builtin_amdgcn_s_sleep(1); \
;     if ((++_sp & 255u) == 0u) { if (xb_ld(&(bar)[XB_TMO])) break; if (_sp > XB_SPIN_CAP) { atomicAdd(&(bar)[XB_TMO], 1u); break; } } } } while (0)
; __device__ __forceinline__ void xcd_barrier(const XcdBarrier& b) {
;     asm volatile("s_waitcnt vmcnt(0)" ::: "memory");
;     __syncthreads();
;     if (threadIdx.x == 0) {
;         unsigned* bar = b.bar;
;         __builtin_amdgcn_s_waitcnt(0);
;         unsigned nloc = b.st[0], nx = b.st[1];
;         if (nloc == 0u) { xcd_barrier_complete(bar, b.x, nloc, nx); b.st[0] = nloc; b.st[1] = nx; }
;         const unsigned old = xb_add(&bar[XB_XSUB(b.x)], 1u);
;         const unsigned gen = old / nloc;
;         if (old + 1u == (gen + 1u) * nloc) {
;             __builtin_amdgcn_fence(__ATOMIC_RELEASE, "agent");
;             asm volatile("s_waitcnt vmcnt(0)" ::: "memory");
;             const unsigned og = xb_add(&bar[XB_TOP], 1u);
;             const unsigned tg = og / nx;
;             if (og + 1u == (tg + 1u) * nx) xb_add(&bar[XB_TOPGEN], 1u);
;             else XB_SPIN(xb_ld(&bar[XB_TOPGEN]) == tg, bar);
;             __builtin_amdgcn_fence(__ATOMIC_ACQUIRE, "agent");
;             xb_add(&bar[XB_XGEN(b.x)], 1u);
.LBB0_684:
	v_readlane_b32 s4, v254, 16
	v_readlane_b32 s18, v254, 30
	v_readlane_b32 s19, v254, 31
	s_mov_b64 s[42:43], s[18:19]
	s_barrier
	s_getreg_b32 s1, hwreg(HW_REG_XCC_ID, 0, 4)
	s_waitcnt vmcnt(0)
	v_readlane_b32 s5, v254, 17
	v_readlane_b32 s6, v254, 18
	v_readlane_b32 s7, v254, 19
	v_readlane_b32 s8, v254, 20
	v_readlane_b32 s9, v254, 21
	v_readlane_b32 s10, v254, 22
	v_readlane_b32 s11, v254, 23
	v_readlane_b32 s12, v254, 24
	v_readlane_b32 s13, v254, 25
	v_readlane_b32 s14, v254, 26
	v_readlane_b32 s15, v254, 27
	v_readlane_b32 s16, v254, 28
	v_readlane_b32 s17, v254, 29
	s_barrier
	s_mov_b64 s[2:3], exec
	v_readlane_b32 s4, v254, 32
	v_readlane_b32 s5, v254, 33
	s_and_b64 s[4:5], s[2:3], s[4:5]
	s_xor_b64 s[34:35], s[4:5], s[2:3]
	s_mov_b64 exec, s[4:5]
	s_cbranch_execz .LBB0_729
	s_waitcnt vmcnt(0) lgkmcnt(0)
	v_mov_b32_e32 v0, 0x20008
	ds_read_b32 v2, v0
	s_waitcnt lgkmcnt(0)
	v_readfirstlane_b32 s4, v2
	s_nop 3
	s_cmp_lg_u32 s4, 0
	s_cbranch_scc1 .Lxk_known_P2
	v_readlane_b32 s10, v254, 30
	v_readlane_b32 s11, v254, 31
	s_nop 3
	s_add_u32 s10, s10, 0x300000
	s_addc_u32 s11, s11, 0
	v_mov_b32_e32 v3, 0
	s_nop 3
	global_load_dword v6, v3, s[10:11] offset:64 sc1
	global_load_dword v7, v3, s[10:11] offset:320 sc1
	global_load_dword v8, v3, s[10:11] offset:576 sc1
	global_load_dword v9, v3, s[10:11] offset:832 sc1
	global_load_dword v10, v3, s[10:11] offset:1088 sc1
	global_load_dword v11, v3, s[10:11] offset:1344 sc1
	global_load_dword v12, v3, s[10:11] offset:1600 sc1
	global_load_dword v13, v3, s[10:11] offset:1856 sc1
	s_waitcnt vmcnt(0)
	v_add_u32_e32 v14, -1, v6
	v_and_b32_e32 v14, v14, v6
	v_add_u32_e32 v15, -1, v7
	v_and_or_b32 v14, v15, v7, v14
	v_add_u32_e32 v15, -1, v8
	v_and_or_b32 v14, v15, v8, v14
	v_add_u32_e32 v15, -1, v9
	v_and_or_b32 v14, v15, v9, v14
	v_add_u32_e32 v15, -1, v10
	v_and_or_b32 v14, v15, v10, v14
	v_add_u32_e32 v15, -1, v11
	v_and_or_b32 v14, v15, v11, v14
	v_add_u32_e32 v15, -1, v12
	v_and_or_b32 v14, v15, v12, v14
	v_add_u32_e32 v15, -1, v13
	v_and_or_b32 v14, v15, v13, v14
	v_add3_u32 v16, v6, v7, v8
	v_add3_u32 v16, v16, v9, v10
	v_add3_u32 v16, v16, v11, v12
	v_add_u32_e32 v16, v16, v13
	v_xor_b32_e32 v16, 0xff, v16
	v_or_b32_e32 v14, v14, v16
	global_load_dword v6, v3, s[10:11] offset:1024 sc1
	global_load_dword v7, v3, s[10:11] offset:1280 sc1
	global_load_dword v8, v3, s[10:11] offset:1536 sc1
	global_load_dword v9, v3, s[10:11] offset:1792 sc1
	global_load_dword v10, v3, s[10:11] offset:2048 sc1
	global_load_dword v11, v3, s[10:11] offset:2304 sc1
	global_load_dword v12, v3, s[10:11] offset:2560 sc1
	global_load_dword v13, v3, s[10:11] offset:2816 sc1
	s_waitcnt vmcnt(0)
	v_xor_b32_e32 v6, 32, v6
	v_xor_b32_e32 v7, 32, v7
	v_xor_b32_e32 v8, 32, v8
	v_xor_b32_e32 v9, 32, v9
	v_xor_b32_e32 v10, 32, v10
	v_xor_b32_e32 v11, 32, v11
	v_xor_b32_e32 v12, 32, v12
	v_xor_b32_e32 v13, 32, v13
	v_or3_b32 v14, v14, v6, v7
	v_or3_b32 v14, v14, v8, v9
	v_or3_b32 v14, v14, v10, v11
	v_or3_b32 v14, v14, v12, v13
	s_nop 1
	v_readfirstlane_b32 s4, v14
	s_nop 3
	s_cmp_eq_u32 s4, 0
	s_cselect_b32 s4, 1, 2
	v_mov_b32_e32 v2, s4
	ds_write_b32 v0, v2
	s_waitcnt lgkmcnt(0)
.Lxk_known_P2:
	s_cmp_eq_u32 s4, 1
	s_cbranch_scc0 .Lxg_P2
	v_readlane_b32 s10, v254, 30
	v_readlane_b32 s11, v254, 31
	s_and_b32 s12, s1, 15
	s_lshl_b32 s12, s12, 8
	s_add_u32 s6, s10, 0x300080
	s_addc_u32 s7, s11, 0
	s_add_u32 s6, s6, s12
	s_addc_u32 s7, s7, 0
	s_add_u32 s12, s10, 0x300008
	s_addc_u32 s13, s11, 0
	v_mov_b32_e32 v6, s12
	v_mov_b32_e32 v7, s13
	v_mov_b32_e32 v8, 1
	flat_atomic_add v[6:7], v8
	v_mov_b32_e32 v2, s6
	v_mov_b32_e32 v3, s7
	v_mov_b32_e32 v4, 1
	flat_atomic_add v4, v[2:3], v4 sc0
	s_mov_b32 s8, 0
	s_waitcnt vmcnt(0) lgkmcnt(0)
	v_and_b32_e32 v4, 0xffffffe0, v4
	v_add_u32_e32 v4, 32, v4

; __device__ __forceinline__ unsigned xb_ld(unsigned* p)              { return __hip_atomic_load(p, __ATOMIC_RELAXED, __HIP_MEMORY_SCOPE_AGENT); }
; __device__ __forceinline__ void xcd_barrier_complete(unsigned* bar, unsigned x, unsigned& nloc, unsigned& nx) {
;     const unsigned G = gridDim.x * gridDim.y * gridDim.z;
;     unsigned sum, cnt, mine, sp = 0u;
;     for (;;) {
;         sum = 0u; cnt = 0u; mine = 0u;
; #pragma unroll
;         for (unsigned j = 0; j < 16; ++j) { const unsigned c = xb_ld(&bar[XB_XCNT(j)]); sum += c; cnt += (c > 0u) ? 1u : 0u; mine = (j == x) ? c : mine; }
;         if (sum == G) break;
;         __builtin_amdgcn_s_sleep(1);
;         if ((++sp & 255u) == 0u) { if (xb_ld(&bar[XB_TMO])) break; if (sp > XB_SPIN_CAP) { atomicAdd(&bar[XB_TMO], 1u); break; } }
;     }
;     nloc = mine > 0u ? mine : 1u; nx = cnt > 0u ? cnt : 1u;
; }
; __device__ __forceinline__ void xcd_barrier(const XcdBarrier& b) {
;     asm volatile("s_waitcnt vmcnt(0)" ::: "memory");
;     __syncthreads();
;     if (threadIdx.x == 0) {
;         unsigned* bar = b.bar;
;         __builtin_amdgcn_s_waitcnt(0);
;         unsigned nloc = b.st[0], nx = b.st[1];
;         if (nloc == 0u) { xcd_barrier_complete(bar, b.x, nloc, nx); b.st[0] = nloc; b.st[1] = nx; }
.Lxg_P2:
	v_readlane_b32 s2, v253, 18
	s_waitcnt vmcnt(0) expcnt(0) lgkmcnt(0)
	s_and_b32 s1, s1, 15
	v_mov_b32_e32 v0, s2
	ds_read_b32 v2, v0
	v_readlane_b32 s2, v253, 19
	s_waitcnt lgkmcnt(0)
	v_cmp_ne_u32_e32 vcc, 0, v2
	v_mov_b32_e32 v0, s2
	ds_read_b32 v0, v0
	s_cbranch_vccnz .LBB0_699
	s_add_u32 s2, s42, 0x300200
	s_addc_u32 s3, s43, 0
	s_add_u32 s4, s42, 0x300400
	s_addc_u32 s5, s43, 0
	s_add_u32 s6, s42, 0x300500
	s_addc_u32 s7, s43, 0
	s_add_u32 s8, s42, 0x300600
	s_addc_u32 s9, s43, 0
	s_add_u32 s10, s42, 0x300700
	s_addc_u32 s11, s43, 0
	s_add_u32 s12, s42, 0x300800
	s_addc_u32 s13, s43, 0
	s_add_u32 s14, s42, 0x300900
	s_addc_u32 s15, s43, 0
	s_add_u32 s16, s42, 0x300a00
	s_addc_u32 s17, s43, 0
	s_add_u32 s18, s42, 0x300b00
	s_addc_u32 s19, s43, 0
	s_add_u32 s20, s42, 0x300c00
	s_addc_u32 s21, s43, 0
	s_add_u32 s22, s42, 0x300d00
	s_addc_u32 s23, s43, 0
	s_add_u32 s24, s42, 0x300e00
	s_addc_u32 s25, s43, 0
	s_add_u32 s26, s42, 0x300f00
	s_addc_u32 s27, s43, 0
	s_add_u32 s28, s42, 0x301000
	s_addc_u32 s29, s43, 0
	s_add_u32 s30, s42, 0x301100
	s_addc_u32 s31, s43, 0
	s_add_u32 s56, s42, 0x301200
	s_addc_u32 s57, s43, 0
	s_add_u32 s72, s42, 0x301300
	s_addc_u32 s73, s43, 0
	s_mov_b32 s39, 1
	s_mov_b64 s[74:75], 0
	s_branch .LBB0_689

; __device__ __forceinline__ unsigned xb_ld(unsigned* p)              { return __hip_atomic_load(p, __ATOMIC_RELAXED, __HIP_MEMORY_SCOPE_AGENT); }
; __device__ __forceinline__ unsigned xb_add(unsigned* p, unsigned v) { return __hip_atomic_fetch_add(p, v, __ATOMIC_RELAXED, __HIP_MEMORY_SCOPE_AGENT); }
; #define XB_SPIN(cond, bar) do { unsigned _sp = 0; while (cond) { __builtin_amdgcn_s_sleep(1); \
;     if ((++_sp & 255u) == 0u) { if (xb_ld(&(bar)[XB_TMO])) break; if (_sp > XB_SPIN_CAP) { atomicAdd(&(bar)[XB_TMO], 1u); break; } } } } while (0)
; __device__ __forceinline__ void xcd_barrier(const XcdBarrier& b) {
;     asm volatile("s_waitcnt vmcnt(0)" ::: "memory");
;     __syncthreads();
;     if (threadIdx.x == 0) {
;         unsigned* bar = b.bar;
;         __builtin_amdgcn_s_waitcnt(0);
;         unsigned nloc = b.st[0], nx = b.st[1];
;         if (nloc == 0u) { xcd_barrier_complete(bar, b.x, nloc, nx); b.st[0] = nloc; b.st[1] = nx; }
;         const unsigned old = xb_add(&bar[XB_XSUB(b.x)], 1u);
;         const unsigned gen = old / nloc;
;         if (old + 1u == (gen + 1u) * nloc) {
;             __builtin_amdgcn_fence(__ATOMIC_RELEASE, "agent");
;             asm volatile("s_waitcnt vmcnt(0)" ::: "memory");
;             const unsigned og = xb_add(&bar[XB_TOP], 1u);
;             const unsigned tg = og / nx;
;             if (og + 1u == (tg + 1u) * nx) xb_add(&bar[XB_TOPGEN], 1u);
;             else XB_SPIN(xb_ld(&bar[XB_TOPGEN]) == tg, bar);
;             __builtin_amdgcn_fence(__ATOMIC_ACQUIRE, "agent");
;             xb_add(&bar[XB_XGEN(b.x)], 1u);
;             asm volatile("s_waitcnt vmcnt(0)" ::: "memory");
;         } else {
;             XB_SPIN(xb_ld(&bar[XB_XGEN(b.x)]) == gen, bar);
;             __builtin_amdgcn_fence(__ATOMIC_ACQUIRE, "agent");
;             asm volatile("s_waitcnt vmcnt(0)" ::: "memory");
.LBB0_867:
	v_readlane_b32 s4, v254, 16
	v_readlane_b32 s18, v254, 30
	v_readlane_b32 s19, v254, 31
	s_mov_b64 s[72:73], s[18:19]
	s_getreg_b32 s1, hwreg(HW_REG_XCC_ID, 0, 4)
	s_waitcnt vmcnt(0)
	v_readlane_b32 s5, v254, 17
	v_readlane_b32 s6, v254, 18
	v_readlane_b32 s7, v254, 19
	v_readlane_b32 s8, v254, 20
	v_readlane_b32 s9, v254, 21
	v_readlane_b32 s10, v254, 22
	v_readlane_b32 s11, v254, 23
	v_readlane_b32 s12, v254, 24
	v_readlane_b32 s13, v254, 25
	v_readlane_b32 s14, v254, 26
	v_readlane_b32 s15, v254, 27
	v_readlane_b32 s16, v254, 28
	v_readlane_b32 s17, v254, 29
	s_barrier
	s_mov_b64 s[42:43], exec
	v_readlane_b32 s4, v254, 32
	v_readlane_b32 s5, v254, 33
	s_and_b64 s[4:5], s[42:43], s[4:5]
	s_mov_b64 exec, s[4:5]
	s_cbranch_execz .LBB0_911
	s_waitcnt vmcnt(0) lgkmcnt(0)
	v_mov_b32_e32 v0, 0x20008
	ds_read_b32 v2, v0
	s_waitcnt lgkmcnt(0)
	v_readfirstlane_b32 s4, v2
	s_nop 3
	s_cmp_eq_u32 s4, 1
	s_cbranch_scc0 .Lxg_P4
	v_readlane_b32 s10, v254, 30
	v_readlane_b32 s11, v254, 31
	s_and_b32 s12, s33, 7
	s_lshr_b32 s13, s33, 3
	s_and_b32 s13, s13, 7
	s_lshl_b32 s12, s12, 3
	s_or_b32 s12, s12, s13
	s_and_b32 s13, s12, 15
	s_lshl_b32 s13, s13, 8
	s_lshr_b32 s12, s12, 4
	s_lshl_b32 s12, s12, 2
	s_add_u32 s12, s12, s13
	s_add_u32 s6, s10, 0x300010
	s_addc_u32 s7, s11, 0
	s_add_u32 s6, s6, s12
	s_addc_u32 s7, s7, 0
	s_add_u32 s12, s10, 0x300008
	s_addc_u32 s13, s11, 0
	v_mov_b32_e32 v6, s12
	v_mov_b32_e32 v7, s13
	v_readlane_b32 s12, v253, 22
	s_nop 3
	s_lshl_b32 s12, s12, 2
	s_add_i32 s12, s12, s44
	s_add_i32 s12, s12, 1
	s_lshl_b32 s12, s12, 8
	v_mov_b32_e32 v9, s12
	v_mov_b32_e32 v2, s6
	v_mov_b32_e32 v3, s7
	v_mov_b32_e32 v4, 1
	flat_atomic_add v4, v[2:3], v4 sc0
	s_mov_b32 s8, 0
	s_waitcnt vmcnt(0) lgkmcnt(0)
	v_and_b32_e32 v4, 0xfffffffc, v4
	v_add_u32_e32 v4, 4, v4
.Lxl_spin_P4:
	flat_load_dword v5, v[2:3] sc1
	flat_load_dword v10, v[6:7] sc1
	s_waitcnt vmcnt(0) lgkmcnt(0)
	v_cmp_lt_u32_e32 vcc, v5, v4
	v_cmp_lt_u32_e64 s[14:15], v10, v9
	s_or_b64 vcc, vcc, s[14:15]
	s_cbranch_vccz .Lxl_done_P4
	s_sleep 1
	s_add_i32 s8, s8, 1
	s_cmp_lt_u32 s8, 0x100000
	s_cbranch_scc1 .Lxl_spin_P4
